# attention epilogue: the sixteen sub-layer-norm gain loads issued at the start of the c=0-only part (right behind the exchange barrier), own address registers
# baseline (speedup 1.0000x reference)
; #define LAS __attribute__((address_space(3)))
; __device__ __forceinline__ unsigned cvt_pk_bf16(float lo, float hi) { unsigned r; asm volatile("v_cvt_pk_bf16_f32 %0, %1, %2" : "=v"(r) : "v"(lo), "v"(hi)); return r; }
; __device__ __forceinline__ float xhalf_sum(float v) { auto rr = __builtin_amdgcn_permlane32_swap(__float_as_uint(v), __float_as_uint(v), false, false); return __uint_as_float(rr[0]) + __uint_as_float(rr[1]); }
; __device__ __forceinline__ void attn_phase(const Args& A, LAS unsigned char* lds, int vcu, int G, const int tid) {
;     ...
;         if (c == 0) {
;             float ss = 0.f;
; #pragma unroll
;             for (int i = 0; i < 4; ++i)
; #pragma unroll
;                 for (int r = 0; r < 16; ++r) { const float d = o[i][r] * inv - scr[(i * 16 + r) * 64 + lane]; o[i][r] = d; ss += d * d; }
;             ss = xhalf_sum(ss);
;             const float rn = (1.0f - LAMBDA_INIT) / sqrtf(ss * (1.0f / 128.0f) + RMS_EPS);
;             int ln = lane; asm volatile("" : "+v"(ln));
;             const int er32 = ln & 31, ehi = ln >> 5;
;             LAS unsigned char* stg = lds + 65536 + qi * (32 * 272);
;             const float* sg = A.in[I_SUBG] + 4 * ehi;
; #pragma unroll
;             for (int i = 0; i < 4; ++i)
; #pragma unroll
;                 for (int rq = 0; rq < 4; ++rq) { const f32x4 gq = *(const f32x4*)(sg + 32 * i + 8 * rq);
;                     u32x2 w; w.x = cvt_pk_bf16(o[i][4 * rq] * rn * gq[0], o[i][4 * rq + 1] * rn * gq[1]); w.y = cvt_pk_bf16(o[i][4 * rq + 2] * rn * gq[2], o[i][4 * rq + 3] * rn * gq[3]);
;                     *(LAS u32x2*)(stg + er32 * 272 + (32 * i + 8 * rq + 4 * ehi) * 2) = w; }
.LBB0_963:
	s_and_b64 vcc, exec, s[4:5]
	s_waitcnt vmcnt(0) lgkmcnt(0)
	s_barrier
	s_cbranch_vccnz .LBB0_839
	v_ashrrev_i32_e32 v156, 3, v201
	v_and_b32_e32 v156, -4, v156
	v_ashrrev_i32_e32 v157, 31, v156
	v_lshl_add_u64 v[158:159], v[156:157], 2, s[76:77]
	global_load_dwordx4 v[160:163], v[158:159], off
	global_load_dwordx4 v[96:99], v[158:159], off offset:32
	global_load_dwordx4 v[100:103], v[158:159], off offset:64
	global_load_dwordx4 v[104:107], v[158:159], off offset:96
	global_load_dwordx4 v[108:111], v[158:159], off offset:128
	global_load_dwordx4 v[112:115], v[158:159], off offset:160
	global_load_dwordx4 v[116:119], v[158:159], off offset:192
	global_load_dwordx4 v[120:123], v[158:159], off offset:224
	global_load_dwordx4 v[124:127], v[158:159], off offset:256
	global_load_dwordx4 v[128:131], v[158:159], off offset:288
	global_load_dwordx4 v[132:135], v[158:159], off offset:320
	global_load_dwordx4 v[136:139], v[158:159], off offset:352
	global_load_dwordx4 v[140:143], v[158:159], off offset:384
	global_load_dwordx4 v[144:147], v[158:159], off offset:416
	global_load_dwordx4 v[148:151], v[158:159], off offset:448
	global_load_dwordx4 v[152:155], v[158:159], off offset:480
	ds_read2st64_b32 v[34:35], v210 offset1:1
	ds_read2st64_b32 v[36:37], v210 offset0:2 offset1:3
	ds_read2st64_b32 v[38:39], v210 offset0:4 offset1:5
	ds_read2st64_b32 v[40:41], v210 offset0:6 offset1:7
	s_ashr_i32 s39, s38, 31
	s_waitcnt lgkmcnt(3)
	v_fma_f32 v33, v80, v32, -v34
	v_fma_f32 v46, v81, v32, -v35
	ds_read2st64_b32 v[34:35], v210 offset0:8 offset1:9
	s_waitcnt lgkmcnt(3)
	v_fma_f32 v48, v82, v32, -v36
	v_fma_f32 v49, v83, v32, -v37
	s_waitcnt lgkmcnt(2)
	v_fma_f32 v50, v84, v32, -v38
	v_fma_f32 v51, v85, v32, -v39
	s_waitcnt lgkmcnt(1)
	v_fma_f32 v52, v86, v32, -v40
	v_fma_f32 v53, v87, v32, -v41
	ds_read2st64_b32 v[36:37], v210 offset0:10 offset1:11
	ds_read2st64_b32 v[38:39], v210 offset0:12 offset1:13
	ds_read2st64_b32 v[40:41], v210 offset0:14 offset1:15
	s_waitcnt lgkmcnt(3)
	v_fma_f32 v54, v88, v32, -v34
	v_fma_f32 v55, v89, v32, -v35
	ds_read2st64_b32 v[34:35], v210 offset0:16 offset1:17
	s_waitcnt lgkmcnt(3)
	v_fma_f32 v56, v90, v32, -v36
	v_fma_f32 v57, v91, v32, -v37
	s_waitcnt lgkmcnt(2)
	v_fma_f32 v58, v92, v32, -v38
	v_fma_f32 v59, v93, v32, -v39
	s_waitcnt lgkmcnt(1)
	v_fma_f32 v60, v94, v32, -v40
	v_fma_f32 v61, v95, v32, -v41
	ds_read2st64_b32 v[36:37], v210 offset0:18 offset1:19
	ds_read2st64_b32 v[38:39], v210 offset0:20 offset1:21
	ds_read2st64_b32 v[40:41], v210 offset0:22 offset1:23
	s_waitcnt lgkmcnt(3)
	v_fma_f32 v62, v64, v32, -v34
	v_fma_f32 v63, v65, v32, -v35
	ds_read2st64_b32 v[34:35], v210 offset0:24 offset1:25
	s_waitcnt lgkmcnt(3)
	v_fma_f32 v64, v66, v32, -v36
	v_fma_f32 v65, v67, v32, -v37
	s_waitcnt lgkmcnt(2)
	v_fma_f32 v66, v68, v32, -v38
	v_fma_f32 v67, v69, v32, -v39
	s_waitcnt lgkmcnt(1)
	v_fma_f32 v68, v70, v32, -v40
	v_fma_f32 v69, v71, v32, -v41
	ds_read2st64_b32 v[36:37], v210 offset0:26 offset1:27
	ds_read2st64_b32 v[38:39], v210 offset0:28 offset1:29
	ds_read2st64_b32 v[40:41], v210 offset0:30 offset1:31
	v_mul_f32_e32 v47, v46, v46
	v_fmac_f32_e32 v47, v33, v33
	v_fmac_f32_e32 v47, v48, v48
	v_fmac_f32_e32 v47, v49, v49
	s_waitcnt lgkmcnt(3)
	v_fma_f32 v70, v72, v32, -v34
	v_fma_f32 v71, v73, v32, -v35
	ds_read2st64_b32 v[34:35], v210 offset0:32 offset1:33
	v_fmac_f32_e32 v47, v50, v50
	s_waitcnt lgkmcnt(3)
	v_fma_f32 v72, v74, v32, -v36
	v_fma_f32 v73, v75, v32, -v37
	s_waitcnt lgkmcnt(2)
	v_fma_f32 v74, v76, v32, -v38
	v_fma_f32 v75, v77, v32, -v39
	s_waitcnt lgkmcnt(1)
	v_fma_f32 v76, v78, v32, -v40
	v_fma_f32 v77, v79, v32, -v41
	ds_read2st64_b32 v[36:37], v210 offset0:34 offset1:35
	ds_read2st64_b32 v[38:39], v210 offset0:36 offset1:37
	ds_read2st64_b32 v[40:41], v210 offset0:38 offset1:39
	v_fmac_f32_e32 v47, v51, v51
	v_fmac_f32_e32 v47, v52, v52
	v_fmac_f32_e32 v47, v53, v53
	v_fmac_f32_e32 v47, v54, v54
	s_waitcnt lgkmcnt(3)
	v_fma_f32 v78, v16, v32, -v34
	v_fma_f32 v79, v17, v32, -v35
	ds_read2st64_b32 v[16:17], v210 offset0:40 offset1:41
	v_fmac_f32_e32 v47, v55, v55
	s_waitcnt lgkmcnt(3)
	v_fma_f32 v80, v18, v32, -v36
	v_fma_f32 v81, v19, v32, -v37
	s_waitcnt lgkmcnt(2)
	v_fma_f32 v82, v20, v32, -v38
	v_fma_f32 v83, v21, v32, -v39
	s_waitcnt lgkmcnt(1)
	v_fma_f32 v84, v22, v32, -v40
	v_fma_f32 v85, v23, v32, -v41
	ds_read2st64_b32 v[18:19], v210 offset0:42 offset1:43
	ds_read2st64_b32 v[20:21], v210 offset0:44 offset1:45
	ds_read2st64_b32 v[22:23], v210 offset0:46 offset1:47
	v_fmac_f32_e32 v47, v56, v56
	v_fmac_f32_e32 v47, v57, v57
	v_fmac_f32_e32 v47, v58, v58
	v_mov_b32_e32 v92, v201
	v_fmac_f32_e32 v47, v59, v59
	s_waitcnt lgkmcnt(3)
	v_fma_f32 v86, v24, v32, -v16
	v_fma_f32 v87, v25, v32, -v17
	s_waitcnt lgkmcnt(2)
	v_fma_f32 v88, v26, v32, -v18
	v_fma_f32 v89, v27, v32, -v19
	s_waitcnt lgkmcnt(1)
; #define LAS __attribute__((address_space(3)))
; __device__ __forceinline__ unsigned cvt_pk_bf16(float lo, float hi) { unsigned r; asm volatile("v_cvt_pk_bf16_f32 %0, %1, %2" : "=v"(r) : "v"(lo), "v"(hi)); return r; }
; __device__ __forceinline__ float xhalf_sum(float v) { auto rr = __builtin_amdgcn_permlane32_swap(__float_as_uint(v), __float_as_uint(v), false, false); return __uint_as_float(rr[0]) + __uint_as_float(rr[1]); }
; __device__ __forceinline__ void attn_phase(const Args& A, LAS unsigned char* lds, int vcu, int G, const int tid) {
;     ...
;         if (c == 0) {
;             float ss = 0.f;
; #pragma unroll
;             for (int i = 0; i < 4; ++i)
; #pragma unroll
;                 for (int r = 0; r < 16; ++r) { const float d = o[i][r] * inv - scr[(i * 16 + r) * 64 + lane]; o[i][r] = d; ss += d * d; }
;             ss = xhalf_sum(ss);
;             const float rn = (1.0f - LAMBDA_INIT) / sqrtf(ss * (1.0f / 128.0f) + RMS_EPS);
;             int ln = lane; asm volatile("" : "+v"(ln));
;             const int er32 = ln & 31, ehi = ln >> 5;
;             LAS unsigned char* stg = lds + 65536 + qi * (32 * 272);
;             const float* sg = A.in[I_SUBG] + 4 * ehi;
; #pragma unroll
;             for (int i = 0; i < 4; ++i)
; #pragma unroll
;                 for (int rq = 0; rq < 4; ++rq) { const f32x4 gq = *(const f32x4*)(sg + 32 * i + 8 * rq);
;                     u32x2 w; w.x = cvt_pk_bf16(o[i][4 * rq] * rn * gq[0], o[i][4 * rq + 1] * rn * gq[1]); w.y = cvt_pk_bf16(o[i][4 * rq + 2] * rn * gq[2], o[i][4 * rq + 3] * rn * gq[3]);
;                     *(LAS u32x2*)(stg + er32 * 272 + (32 * i + 8 * rq + 4 * ehi) * 2) = w; }
	v_fma_f32 v90, v28, v32, -v20
	v_fma_f32 v91, v29, v32, -v21
	ds_read2st64_b32 v[24:25], v210 offset0:48 offset1:49
	ds_read2st64_b32 v[26:27], v210 offset0:50 offset1:51
	ds_read2st64_b32 v[28:29], v210 offset0:52 offset1:53
	ds_read2st64_b32 v[34:35], v210 offset0:54 offset1:55
	ds_read2st64_b32 v[36:37], v210 offset0:56 offset1:57
	ds_read2st64_b32 v[38:39], v210 offset0:58 offset1:59
	ds_read2st64_b32 v[40:41], v210 offset0:60 offset1:61
	ds_read2st64_b32 v[42:43], v210 offset0:62 offset1:63
	v_fmac_f32_e32 v47, v60, v60
	v_ashrrev_i32_e32 v16, 3, v92
	v_and_b32_e32 v44, -4, v16
	v_fmac_f32_e32 v47, v61, v61
	v_ashrrev_i32_e32 v45, 31, v44
	v_fmac_f32_e32 v47, v62, v62
	v_lshl_add_u64 v[16:17], v[44:45], 2, s[76:77]
	v_fmac_f32_e32 v47, v63, v63
	v_fmac_f32_e32 v47, v64, v64
	v_fmac_f32_e32 v47, v65, v65
	v_fmac_f32_e32 v47, v66, v66
	v_fmac_f32_e32 v47, v67, v67
	v_fmac_f32_e32 v47, v68, v68
	v_fmac_f32_e32 v47, v69, v69
	v_fmac_f32_e32 v47, v70, v70
	v_fmac_f32_e32 v47, v71, v71
	v_fmac_f32_e32 v47, v72, v72
	v_fmac_f32_e32 v47, v73, v73
	v_fmac_f32_e32 v47, v74, v74
	v_fmac_f32_e32 v47, v75, v75
	v_fmac_f32_e32 v47, v76, v76
	v_fmac_f32_e32 v47, v77, v77
	v_fmac_f32_e32 v47, v78, v78
	v_fmac_f32_e32 v47, v79, v79
	v_fmac_f32_e32 v47, v80, v80
	v_fmac_f32_e32 v47, v81, v81
	v_fmac_f32_e32 v47, v82, v82
	v_fmac_f32_e32 v47, v83, v83
	v_fmac_f32_e32 v47, v84, v84
	v_fmac_f32_e32 v47, v85, v85
	v_fmac_f32_e32 v47, v86, v86
	v_fmac_f32_e32 v47, v87, v87
	v_fmac_f32_e32 v47, v88, v88
	v_fmac_f32_e32 v47, v89, v89
	v_fmac_f32_e32 v47, v90, v90
	v_fmac_f32_e32 v47, v91, v91
	s_waitcnt lgkmcnt(8)
	v_fma_f32 v22, v30, v32, -v22
	v_fmac_f32_e32 v47, v22, v22
	v_fma_f32 v23, v31, v32, -v23
	v_fmac_f32_e32 v47, v23, v23
	s_waitcnt lgkmcnt(7)
	v_fma_f32 v24, v0, v32, -v24
	v_fmac_f32_e32 v47, v24, v24
	v_fma_f32 v25, v1, v32, -v25
	v_fmac_f32_e32 v47, v25, v25
	s_waitcnt lgkmcnt(6)
	v_fma_f32 v26, v2, v32, -v26
	v_fmac_f32_e32 v47, v26, v26
	v_fma_f32 v27, v3, v32, -v27
	v_fmac_f32_e32 v47, v27, v27
	s_waitcnt lgkmcnt(5)
	v_fma_f32 v28, v4, v32, -v28
	v_fmac_f32_e32 v47, v28, v28
	v_fma_f32 v29, v5, v32, -v29
	v_fmac_f32_e32 v47, v29, v29
	s_waitcnt lgkmcnt(4)
	v_fma_f32 v6, v6, v32, -v34
	v_fmac_f32_e32 v47, v6, v6
	v_fma_f32 v7, v7, v32, -v35
	v_fmac_f32_e32 v47, v7, v7
	s_waitcnt lgkmcnt(3)
	v_fma_f32 v8, v8, v32, -v36
	v_fmac_f32_e32 v47, v8, v8
	v_fma_f32 v9, v9, v32, -v37
	v_fmac_f32_e32 v47, v9, v9
	s_waitcnt lgkmcnt(2)
	v_fma_f32 v10, v10, v32, -v38
	v_fmac_f32_e32 v47, v10, v10
	v_fma_f32 v11, v11, v32, -v39
	v_fmac_f32_e32 v47, v11, v11
	s_waitcnt lgkmcnt(1)
	v_fma_f32 v30, v12, v32, -v40
	v_fmac_f32_e32 v47, v30, v30
	v_fma_f32 v13, v13, v32, -v41
	v_fmac_f32_e32 v47, v13, v13
	s_waitcnt lgkmcnt(0)
	v_fma_f32 v14, v14, v32, -v42
	v_fmac_f32_e32 v47, v14, v14
	v_fma_f32 v15, v15, v32, -v43
	v_fmac_f32_e32 v47, v15, v15
	v_mov_b32_e32 v0, v47
	s_nop 1
	v_permlane32_swap_b32_e32 v47, v0
	v_add_f32_e32 v0, v47, v0
	v_fmamk_f32 v0, v0, 0x3c000000, v215
	v_mul_f32_e32 v1, 0x4f800000, v0
	v_cmp_gt_f32_e32 vcc, s9, v0
	v_and_b32_e32 v12, 31, v92
	v_mul_u32_u24_e32 v12, 0x110, v12
	v_cndmask_b32_e32 v0, v0, v1, vcc
	v_sqrt_f32_e32 v1, v0
	s_movk_i32 s12, 0x4000
	v_add_u32_e32 v2, -1, v1
	v_fma_f32 v3, -v2, v1, v0
	v_cmp_ge_f32_e64 s[4:5], 0, v3
	v_add_u32_e32 v3, 1, v1
	s_nop 0
	v_cndmask_b32_e64 v2, v1, v2, s[4:5]
	v_fma_f32 v1, -v3, v1, v0
	v_cmp_lt_f32_e64 s[4:5], 0, v1
	s_nop 1
	v_cndmask_b32_e64 v1, v2, v3, s[4:5]
	v_mul_f32_e32 v2, 0x37800000, v1
	v_cndmask_b32_e32 v1, v1, v2, vcc
	v_cmp_class_f32_e32 vcc, v0, v202
	s_movk_i32 s4, 0x110
	s_movk_i32 s5, 0x2000
	v_cndmask_b32_e32 v0, v1, v0, vcc
	v_div_scale_f32 v1, s[2:3], v0, v0, s63
	v_rcp_f32_e32 v2, v1
	s_lshl_b64 s[2:3], s[38:39], 11
	s_add_u32 s13, s18, s2
	s_addc_u32 s14, s19, s3
	v_fma_f32 v3, -v1, v2, 1.0
	v_fmac_f32_e32 v2, v3, v2
	v_div_scale_f32 v3, vcc, s63, v0, s63
	v_mul_f32_e32 v4, v3, v2
	v_fma_f32 v5, -v1, v4, v3
	v_fmac_f32_e32 v4, v5, v2
	v_fma_f32 v1, -v1, v4, v3
	v_div_fmas_f32 v1, v1, v2, v4
	v_div_fixup_f32 v31, v1, v0, s63
	v_mul_f32_e32 v0, v33, v31
	v_mul_f32_e32 v1, v46, v31
	s_waitcnt vmcnt(0)
	v_mov_b64_e32 v[18:19], v[160:161]
	v_mov_b64_e32 v[20:21], v[162:163]
	v_mul_f32_e32 v0, v18, v0
	v_mul_f32_e32 v1, v19, v1
	v_cvt_pk_bf16_f32 v4, v0, v1
	v_mul_f32_e32 v0, v48, v31
	v_mul_f32_e32 v1, v49, v31
	v_mul_f32_e32 v0, v20, v0
	v_mul_f32_e32 v1, v21, v1
	v_cvt_pk_bf16_f32 v5, v0, v1
	v_lshlrev_b32_e32 v18, 1, v44
	v_add3_u32 v18, s60, v12, v18
	ds_write_b64 v18, v[4:5]
	v_mul_f32_e32 v4, v50, v31
	v_mul_f32_e32 v12, v54, v31
	v_mul_f32_e32 v19, v55, v31
	v_mul_f32_e32 v20, v56, v31
	v_mul_f32_e32 v21, v57, v31
	v_mul_f32_e32 v6, v6, v31
	v_mul_f32_e32 v7, v7, v31
	s_lshl_b64 s[2:3], s[36:37], 1
	s_add_u32 s2, s13, s2
	s_addc_u32 s3, s14, s3
	v_mov_b64_e32 v[0:1], v[96:97]
	v_mov_b64_e32 v[2:3], v[98:99]
	v_mul_f32_e32 v0, v0, v4
	v_mul_f32_e32 v4, v51, v31
	v_mul_f32_e32 v1, v1, v4
	v_cvt_pk_bf16_f32 v4, v0, v1
	v_mul_f32_e32 v0, v52, v31
	v_mul_f32_e32 v1, v53, v31
	v_mul_f32_e32 v0, v2, v0
	v_mul_f32_e32 v1, v3, v1
	v_cvt_pk_bf16_f32 v5, v0, v1
	ds_write_b64 v18, v[4:5] offset:16
	v_mov_b64_e32 v[0:1], v[100:101]
	v_mov_b64_e32 v[2:3], v[102:103]
	v_mul_f32_e32 v0, v12, v0
	v_mul_f32_e32 v1, v19, v1
	v_mul_f32_e32 v2, v20, v2
	v_mul_f32_e32 v3, v21, v3
	v_cvt_pk_bf16_f32 v4, v0, v1
	v_cvt_pk_bf16_f32 v5, v2, v3
	v_mul_f32_e32 v12, v58, v31
	v_mul_f32_e32 v19, v59, v31
	v_mul_f32_e32 v20, v60, v31
	v_mul_f32_e32 v21, v61, v31
	ds_write_b64 v18, v[4:5] offset:32
	v_mov_b64_e32 v[0:1], v[104:105]
	v_mov_b64_e32 v[2:3], v[106:107]
	v_mul_f32_e32 v0, v12, v0
; #define LAS __attribute__((address_space(3)))
; __device__ __forceinline__ unsigned cvt_pk_bf16(float lo, float hi) { unsigned r; asm volatile("v_cvt_pk_bf16_f32 %0, %1, %2" : "=v"(r) : "v"(lo), "v"(hi)); return r; }
; __device__ __forceinline__ void attn_phase(const Args& A, LAS unsigned char* lds, int vcu, int G, const int tid) {
;     ...
;             for (int i = 0; i < 4; ++i)
; #pragma unroll
;                 for (int rq = 0; rq < 4; ++rq) { const f32x4 gq = *(const f32x4*)(sg + 32 * i + 8 * rq);
;                     u32x2 w; w.x = cvt_pk_bf16(o[i][4 * rq] * rn * gq[0], o[i][4 * rq + 1] * rn * gq[1]); w.y = cvt_pk_bf16(o[i][4 * rq + 2] * rn * gq[2], o[i][4 * rq + 3] * rn * gq[3]);
;                     *(LAS u32x2*)(stg + er32 * 272 + (32 * i + 8 * rq + 4 * ehi) * 2) = w; }
;             asm volatile("s_waitcnt lgkmcnt(0)" ::: "memory");
;             bf16_t* obase = AO + (size_t)(qrow - r32) * DM + h * 128;
; #pragma unroll
;             for (int k = 0; k < 8; ++k) { const int row = 4 * k + (ln >> 4), ch = ln & 15;
;                 const u32x4 v = *(const LAS u32x4*)(stg + row * 272 + ch * 16);
;                 *(u32x4*)(obase + (size_t)row * DM + ch * 8) = v;
;                 if (k & 1) asm volatile("" ::: "memory"); }
	v_mul_f32_e32 v1, v19, v1
	v_mul_f32_e32 v2, v20, v2
	v_mul_f32_e32 v3, v21, v3
	v_cvt_pk_bf16_f32 v4, v0, v1
	v_cvt_pk_bf16_f32 v5, v2, v3
	v_mul_f32_e32 v12, v62, v31
	v_mul_f32_e32 v19, v63, v31
	v_mul_f32_e32 v20, v64, v31
	v_mul_f32_e32 v21, v65, v31
	ds_write_b64 v18, v[4:5] offset:48
	v_mov_b64_e32 v[0:1], v[108:109]
	v_mov_b64_e32 v[2:3], v[110:111]
	v_mul_f32_e32 v0, v12, v0
	v_mul_f32_e32 v1, v19, v1
	v_mul_f32_e32 v2, v20, v2
	v_mul_f32_e32 v3, v21, v3
	v_cvt_pk_bf16_f32 v4, v0, v1
	v_cvt_pk_bf16_f32 v5, v2, v3
	v_mul_f32_e32 v12, v66, v31
	v_mul_f32_e32 v19, v67, v31
	v_mul_f32_e32 v20, v68, v31
	v_mul_f32_e32 v21, v69, v31
	ds_write_b64 v18, v[4:5] offset:64
	v_mov_b64_e32 v[0:1], v[112:113]
	v_mov_b64_e32 v[2:3], v[114:115]
	v_mul_f32_e32 v0, v12, v0
	v_mul_f32_e32 v1, v19, v1
	v_mul_f32_e32 v2, v20, v2
	v_mul_f32_e32 v3, v21, v3
	v_cvt_pk_bf16_f32 v4, v0, v1
	v_cvt_pk_bf16_f32 v5, v2, v3
	v_mul_f32_e32 v12, v70, v31
	v_mul_f32_e32 v19, v71, v31
	v_mul_f32_e32 v20, v72, v31
	v_mul_f32_e32 v21, v73, v31
	ds_write_b64 v18, v[4:5] offset:80
	v_mov_b64_e32 v[0:1], v[116:117]
	v_mov_b64_e32 v[2:3], v[118:119]
	v_mul_f32_e32 v0, v12, v0
	v_mul_f32_e32 v1, v19, v1
	v_mul_f32_e32 v2, v20, v2
	v_mul_f32_e32 v3, v21, v3
	v_cvt_pk_bf16_f32 v4, v0, v1
	v_cvt_pk_bf16_f32 v5, v2, v3
	v_mul_f32_e32 v12, v74, v31
	v_mul_f32_e32 v19, v75, v31
	v_mul_f32_e32 v20, v76, v31
	v_mul_f32_e32 v21, v77, v31
	ds_write_b64 v18, v[4:5] offset:96
	v_mov_b64_e32 v[0:1], v[120:121]
	v_mov_b64_e32 v[2:3], v[122:123]
	v_mul_f32_e32 v0, v12, v0
	v_mul_f32_e32 v1, v19, v1
	v_mul_f32_e32 v2, v20, v2
	v_mul_f32_e32 v3, v21, v3
	v_cvt_pk_bf16_f32 v4, v0, v1
	v_cvt_pk_bf16_f32 v5, v2, v3
	v_mul_f32_e32 v12, v78, v31
	v_mul_f32_e32 v19, v79, v31
	v_mul_f32_e32 v20, v80, v31
	v_mul_f32_e32 v21, v81, v31
	ds_write_b64 v18, v[4:5] offset:112
	v_mov_b64_e32 v[0:1], v[124:125]
	v_mov_b64_e32 v[2:3], v[126:127]
	v_mul_f32_e32 v0, v12, v0
	v_mul_f32_e32 v1, v19, v1
	v_mul_f32_e32 v2, v20, v2
	v_mul_f32_e32 v3, v21, v3
	v_cvt_pk_bf16_f32 v4, v0, v1
	v_cvt_pk_bf16_f32 v5, v2, v3
	v_mul_f32_e32 v12, v82, v31
	v_mul_f32_e32 v19, v83, v31
	v_mul_f32_e32 v20, v84, v31
	v_mul_f32_e32 v21, v85, v31
	ds_write_b64 v18, v[4:5] offset:128
	v_mov_b64_e32 v[0:1], v[128:129]
	v_mov_b64_e32 v[2:3], v[130:131]
	v_mul_f32_e32 v0, v12, v0
	v_mul_f32_e32 v1, v19, v1
	v_mul_f32_e32 v2, v20, v2
	v_mul_f32_e32 v3, v21, v3
	v_cvt_pk_bf16_f32 v4, v0, v1
	v_cvt_pk_bf16_f32 v5, v2, v3
	v_mul_f32_e32 v12, v86, v31
	v_mul_f32_e32 v19, v87, v31
	v_mul_f32_e32 v20, v88, v31
	v_mul_f32_e32 v21, v89, v31
	ds_write_b64 v18, v[4:5] offset:144
	v_mov_b64_e32 v[0:1], v[132:133]
	v_mov_b64_e32 v[2:3], v[134:135]
	v_mul_f32_e32 v0, v12, v0
	v_mul_f32_e32 v1, v19, v1
	v_mul_f32_e32 v2, v20, v2
	v_mul_f32_e32 v3, v21, v3
	v_cvt_pk_bf16_f32 v4, v0, v1
	v_cvt_pk_bf16_f32 v5, v2, v3
	v_mul_f32_e32 v12, v90, v31
	v_mul_f32_e32 v19, v91, v31
	v_mul_f32_e32 v20, v22, v31
	v_mul_f32_e32 v21, v23, v31
	ds_write_b64 v18, v[4:5] offset:160
	v_mov_b64_e32 v[0:1], v[136:137]
	v_mov_b64_e32 v[2:3], v[138:139]
	v_mul_f32_e32 v0, v12, v0
	v_mul_f32_e32 v1, v19, v1
	v_mul_f32_e32 v2, v20, v2
	v_mul_f32_e32 v3, v21, v3
	v_cvt_pk_bf16_f32 v4, v0, v1
	v_cvt_pk_bf16_f32 v5, v2, v3
	v_mul_f32_e32 v12, v24, v31
	v_mul_f32_e32 v19, v25, v31
	v_mul_f32_e32 v20, v26, v31
	v_mul_f32_e32 v21, v27, v31
	ds_write_b64 v18, v[4:5] offset:176
	v_mov_b64_e32 v[0:1], v[140:141]
	v_mov_b64_e32 v[2:3], v[142:143]
	v_mul_f32_e32 v0, v12, v0
	v_mul_f32_e32 v1, v19, v1
	v_mul_f32_e32 v2, v20, v2
	v_mul_f32_e32 v3, v21, v3
	v_cvt_pk_bf16_f32 v4, v0, v1
	v_cvt_pk_bf16_f32 v5, v2, v3
	v_mul_f32_e32 v12, v28, v31
	v_mul_f32_e32 v19, v29, v31
	ds_write_b64 v18, v[4:5] offset:192
	v_mov_b64_e32 v[0:1], v[144:145]
	v_mov_b64_e32 v[2:3], v[146:147]
	v_mul_f32_e32 v0, v12, v0
	v_mul_f32_e32 v1, v19, v1
	v_mul_f32_e32 v2, v6, v2
	v_mul_f32_e32 v3, v7, v3
	v_cvt_pk_bf16_f32 v4, v0, v1
	v_cvt_pk_bf16_f32 v5, v2, v3
	v_mul_f32_e32 v6, v8, v31
	v_mul_f32_e32 v7, v9, v31
	v_mul_f32_e32 v8, v10, v31
	v_mul_f32_e32 v9, v11, v31
	ds_write_b64 v18, v[4:5] offset:208
	v_mul_f32_e32 v19, v15, v31
	v_mov_b64_e32 v[0:1], v[148:149]
	v_mov_b64_e32 v[2:3], v[150:151]
	v_mul_f32_e32 v0, v6, v0
	v_mul_f32_e32 v1, v7, v1
	v_mul_f32_e32 v2, v8, v2
	v_mul_f32_e32 v3, v9, v3
	v_cvt_pk_bf16_f32 v4, v0, v1
	v_cvt_pk_bf16_f32 v5, v2, v3
	v_ashrrev_i32_e32 v8, 4, v92
	v_lshlrev_b32_e32 v6, 4, v92
	v_mov_b32_e32 v7, v191
	v_and_b32_e32 v6, 0xf0, v6
	v_mul_lo_u32 v10, v8, s4
	v_ashrrev_i32_e32 v9, 31, v8
	v_add3_u32 v20, s60, v6, v10
	v_lshlrev_b64 v[8:9], 11, v[8:9]
	v_lshl_add_u64 v[6:7], s[2:3], 0, v[6:7]
	v_lshl_add_u64 v[8:9], v[6:7], 0, v[8:9]
	v_mul_f32_e32 v6, v30, v31
	v_mul_f32_e32 v7, v13, v31
	v_mul_f32_e32 v17, v14, v31
	ds_write_b64 v18, v[4:5] offset:224
	v_add_co_u32_e32 v10, vcc, s5, v8
	v_mov_b64_e32 v[0:1], v[152:153]
	v_mov_b64_e32 v[2:3], v[154:155]
	v_mul_f32_e32 v0, v6, v0
	v_mul_f32_e32 v1, v7, v1
	v_mul_f32_e32 v2, v17, v2
	v_mul_f32_e32 v3, v19, v3
	v_cvt_pk_bf16_f32 v0, v0, v1
	v_cvt_pk_bf16_f32 v1, v2, v3
	ds_write_b64 v18, v[0:1] offset:240
	s_waitcnt lgkmcnt(0)
	ds_read_b128 v[0:3], v20
	ds_read_b128 v[4:7], v20 offset:1088
	v_addc_co_u32_e32 v11, vcc, 0, v9, vcc
	s_waitcnt lgkmcnt(1)
	global_store_dwordx4 v[8:9], v[0:3], off
	s_waitcnt lgkmcnt(0)
	global_store_dwordx4 v[10:11], v[4:7], off
	ds_read_b128 v[0:3], v20 offset:2176
	ds_read_b128 v[4:7], v20 offset:3264
	v_add_co_u32_e32 v12, vcc, s12, v8
	s_nop 1
	v_addc_co_u32_e32 v13, vcc, 0, v9, vcc
	v_add_co_u32_e32 v14, vcc, 0x6000, v8
	s_nop 1
	v_addc_co_u32_e32 v15, vcc, 0, v9, vcc
	s_waitcnt lgkmcnt(1)
	global_store_dwordx4 v[12:13], v[0:3], off
	s_waitcnt lgkmcnt(0)
	global_store_dwordx4 v[14:15], v[4:7], off
	ds_read_b128 v[0:3], v20 offset:4352
	ds_read_b128 v[4:7], v20 offset:5440
	v_add_co_u32_e32 v16, vcc, 0x8000, v8
	s_nop 1
	v_addc_co_u32_e32 v17, vcc, 0, v9, vcc
	v_add_co_u32_e32 v18, vcc, 0xa000, v8
	s_nop 1
	v_addc_co_u32_e32 v19, vcc, 0, v9, vcc
	s_waitcnt lgkmcnt(1)
	global_store_dwordx4 v[16:17], v[0:3], off
	s_waitcnt lgkmcnt(0)
	global_store_dwordx4 v[18:19], v[4:7], off
	ds_read_b128 v[0:3], v20 offset:6528
	ds_read_b128 v[4:7], v20 offset:7616
	v_add_co_u32_e32 v10, vcc, 0xc000, v8
	s_nop 1
	v_addc_co_u32_e32 v11, vcc, 0, v9, vcc
	v_add_co_u32_e32 v8, vcc, 0xe000, v8
	s_nop 1
	v_addc_co_u32_e32 v9, vcc, 0, v9, vcc
	s_waitcnt lgkmcnt(1)
	global_store_dwordx4 v[10:11], v[0:3], off
	s_waitcnt lgkmcnt(0)
	global_store_dwordx4 v[8:9], v[4:7], off
	s_branch .LBB0_839
